# GEMM phase tail: the store-drain waits ahead of the sample-row small GEMM dropped at 7 sites (LDS-DMA stages are provably older than waited epilogue loads), small-GEMM loads overlap the drain
# speedup vs baseline: 1.0063x; 1.0050x over previous
; #define PG8_WAIT_V(n) asm volatile("s_waitcnt vmcnt(" #n ")" ::: "memory")
; #define PG8_BAR __builtin_amdgcn_s_barrier()
; template <class Epi>
; __device__ __forceinline__ void gemm_phase(LAS unsigned char* lds, const Gemm g, const StaticOrder& S, const Epi& E) {
;     ...
;     PG8_WAIT_V(0);
;     if (wr == 0) PG8_BAR;
;     PG8_BAR;
.LBB0_1459:
	s_cmpk_gt_u32 s3, 0xff
	s_cbranch_scc1 .LBB0_1461
	s_barrier

;     int tid = threadIdx.x; asm volatile("" : "+v"(tid));
;     const int wid = tid >> 6, lane = tid & 63, fr = lane & 15, fq = lane >> 4;
;     float* part = (float*)lds;
;     const int kw = K >> 3, ksteps = kw >> 5;
;     if (first < 0) { first = blockIdx.x; stride = gridDim.x; }
;     for (int tile = first; tile < 8 * ncol_tiles; tile += stride) {
;         const int rt = tile & 7, ct = tile >> 3, r0 = MP_ROWS + 32 * rt, c0 = 32 * ct;
;         const bf16_t* ap = A + (size_t)(r0 + fr) * lda + (c0 >> 8) * a_grp_off + wid * kw + 8 * fq;
;         const bf16_t* bp = Bt + (size_t)(c0 + fr) * ldb + wid * kw + 8 * fq;
;     ...
;             for (int j = 0; j < 2; ++j) *(f32x4*)(part + (wid * 32 + 16 * i + fr) * 36 + 16 * j + 4 * fq) = acc[i][j];
;         __syncthreads();
;         if (tid < 128) { const int row = tid >> 2, oct = tid & 3; f32x4 v0 = (f32x4){0.f, 0.f, 0.f, 0.f}, v1 = v0;
; #pragma unroll
;             for (int w = 0; w < 8; ++w) { v0 += *(const f32x4*)(part + (w * 32 + row) * 36 + 8 * oct); v1 += *(const f32x4*)(part + (w * 32 + row) * 36 + 8 * oct + 4); }
.LBB0_1773:
	v_mov_b32_e32 v7, v210
	s_and_b64 vcc, exec, s[6:7]
	s_cbranch_vccnz .LBB0_1779
	v_ashrrev_i32_e32 v6, 6, v7
	v_lshlrev_b32_e32 v0, 7, v6
	s_waitcnt lgkmcnt(0)
	v_ashrrev_i32_e32 v1, 31, v0
	v_and_b32_e32 v10, 15, v7
	v_lshlrev_b64 v[4:5], 1, v[0:1]
	s_movk_i32 s3, 0x80
	v_lshl_add_u64 v[2:3], s[68:69], 0, v[4:5]
	v_and_b32_e32 v0, 48, v7
	v_mov_b32_e32 v1, 0
	v_lshl_add_u64 v[4:5], s[18:19], 0, v[4:5]
	v_lshl_or_b32 v8, v6, 5, v10
	v_cmp_gt_i32_e64 s[6:7], s3, v7
	v_ashrrev_i32_e32 v6, 2, v7
	v_and_b32_e32 v7, 3, v7
	s_movk_i32 s3, 0x90
	v_lshl_add_u64 v[2:3], v[2:3], 0, v[0:1]
	v_lshl_add_u64 v[4:5], v[4:5], 0, v[0:1]
	v_add_u32_e32 v0, 0, v0
	v_lshl_add_u32 v12, v7, 5, 0
	v_lshlrev_b32_e32 v11, 3, v7
	v_cmp_eq_u32_e64 s[8:9], 0, v7
	v_ashrrev_i32_e32 v7, 31, v6
	v_mul_lo_u32 v13, v8, s3
	v_mul_lo_u32 v14, v6, s3
	v_lshl_add_u64 v[8:9], v[6:7], 2, s[16:17]
	v_add_u32_e32 v7, v0, v13
	v_mbcnt_lo_u32_b32 v0, -1, 0
	s_mov_b32 s11, 0
	s_lshl_b32 s3, s2, 2
	s_lshl_b32 s16, s58, 2
	s_lshl_b32 s17, s2, 5
	s_lshl_b32 s18, s58, 5
	s_mov_b32 s19, 0x8000
	v_add_u32_e32 v12, v12, v14
	v_mov_b32_e32 v13, 0x358637bd
	s_mov_b32 s20, 0x800000
	v_mbcnt_hi_u32_b32 v14, -1, v0
	s_mov_b32 s21, s2
	s_branch .LBB0_1776
